# removed 18 duplicate lgkmcnt(0) waits (same wait two lines above) in the three GEMM K-loops
# speedup vs baseline: 1.0248x; 1.0248x over previous
.LBB0_234:
	ds_read_b128 v[136:139], v167
	ds_read_b128 v[140:143], v167 offset:1024
	ds_read_b128 v[144:147], v167 offset:2048
	ds_read_b128 v[148:151], v167 offset:3072
	s_add_u32 s3, s10, 0xfff80080
	s_addc_u32 s28, s11, -1
	s_cmp_eq_u32 vcc_lo, 28
	s_cselect_b32 s35, s9, s28
	s_cselect_b32 s34, s89, s3
	s_cselect_b32 s29, s71, s95
	s_cselect_b32 s28, s91, s93
	v_lshl_add_u64 v[152:153], s[10:11], 0, v[132:133]
	s_add_i32 m0, s62, 0xc000
	ds_read_b128 v[172:175], v168
	ds_read_b128 v[190:193], v168 offset:1024
	ds_read_b128 v[194:197], v168 offset:2048
	ds_read_b128 v[198:201], v168 offset:3072
	ds_read_b128 v[202:205], v168 offset:4096
	ds_read_b128 v[206:209], v168 offset:5120
	ds_read_b128 v[224:227], v168 offset:6144
	ds_read_b128 v[228:231], v168 offset:7168
	global_load_lds_dwordx4 v[152:153], off
	v_lshl_add_u64 v[152:153], s[10:11], 0, v[134:135]
	s_add_i32 m0, s62, 0xe000
	s_nop 0
	global_load_lds_dwordx4 v[152:153], off
	s_waitcnt lgkmcnt(8)
	s_barrier
	s_waitcnt lgkmcnt(0)
	s_setprio 1
	v_mfma_f32_16x16x32_bf16 v[124:127], v[136:139], v[172:175], v[124:127]
	v_mfma_f32_16x16x32_bf16 v[116:119], v[144:147], v[172:175], v[116:119]
	v_mfma_f32_16x16x32_bf16 v[108:111], v[136:139], v[194:197], v[108:111]
	v_mfma_f32_16x16x32_bf16 v[100:103], v[144:147], v[194:197], v[100:103]
	v_mfma_f32_16x16x32_bf16 v[92:95], v[136:139], v[202:205], v[92:95]
	v_mfma_f32_16x16x32_bf16 v[84:87], v[144:147], v[202:205], v[84:87]
	v_mfma_f32_16x16x32_bf16 v[76:79], v[136:139], v[224:227], v[76:79]
	v_mfma_f32_16x16x32_bf16 v[68:71], v[144:147], v[224:227], v[68:71]
	v_mfma_f32_16x16x32_bf16 v[124:127], v[140:143], v[190:193], v[124:127]
	v_mfma_f32_16x16x32_bf16 v[116:119], v[148:151], v[190:193], v[116:119]
	v_mfma_f32_16x16x32_bf16 v[108:111], v[140:143], v[198:201], v[108:111]
	v_mfma_f32_16x16x32_bf16 v[100:103], v[148:151], v[198:201], v[100:103]
	v_mfma_f32_16x16x32_bf16 v[92:95], v[140:143], v[206:209], v[92:95]
	v_mfma_f32_16x16x32_bf16 v[84:87], v[148:151], v[206:209], v[84:87]
	v_mfma_f32_16x16x32_bf16 v[76:79], v[140:143], v[228:231], v[76:79]
	v_mfma_f32_16x16x32_bf16 v[68:71], v[148:151], v[228:231], v[68:71]
	s_setprio 0
	s_barrier
	s_add_i32 s3, s84, s61
	v_lshl_add_u64 v[152:153], s[28:29], 0, v[184:185]
	s_mov_b32 m0, s3
	ds_read_b128 v[232:235], v169
	ds_read_b128 v[236:239], v169 offset:1024
	ds_read_b128 v[240:243], v169 offset:2048
	ds_read_b128 v[244:247], v169 offset:3072
	global_load_lds_dwordx4 v[152:153], off
	v_lshl_add_u64 v[248:249], s[28:29], 0, v[188:189]
	s_add_i32 m0, s3, 0x2000
	s_nop 0
	global_load_lds_dwordx4 v[248:249], off
	s_barrier
	s_waitcnt lgkmcnt(0)
	s_setprio 1
	v_mfma_f32_16x16x32_bf16 v[120:123], v[232:235], v[172:175], v[120:123]
	v_mfma_f32_16x16x32_bf16 v[112:115], v[240:243], v[172:175], v[112:115]
	v_mfma_f32_16x16x32_bf16 v[104:107], v[232:235], v[194:197], v[104:107]
	v_mfma_f32_16x16x32_bf16 v[96:99], v[240:243], v[194:197], v[96:99]
	v_mfma_f32_16x16x32_bf16 v[88:91], v[232:235], v[202:205], v[88:91]
	v_mfma_f32_16x16x32_bf16 v[80:83], v[240:243], v[202:205], v[80:83]
	v_mfma_f32_16x16x32_bf16 v[72:75], v[232:235], v[224:227], v[72:75]
	v_mfma_f32_16x16x32_bf16 v[64:67], v[240:243], v[224:227], v[64:67]
	v_mfma_f32_16x16x32_bf16 v[120:123], v[236:239], v[190:193], v[120:123]
	v_mfma_f32_16x16x32_bf16 v[112:115], v[244:247], v[190:193], v[112:115]
	v_mfma_f32_16x16x32_bf16 v[104:107], v[236:239], v[198:201], v[104:107]
	v_mfma_f32_16x16x32_bf16 v[96:99], v[244:247], v[198:201], v[96:99]
	v_mfma_f32_16x16x32_bf16 v[88:91], v[236:239], v[206:209], v[88:91]
	v_mfma_f32_16x16x32_bf16 v[80:83], v[244:247], v[206:209], v[80:83]
	v_mfma_f32_16x16x32_bf16 v[72:75], v[236:239], v[228:231], v[72:75]
	v_mfma_f32_16x16x32_bf16 v[64:67], v[244:247], v[228:231], v[64:67]
	s_setprio 0
	s_mov_b32 m0, s62
	v_lshl_add_u64 v[250:251], s[34:35], 0, v[182:183]
	s_barrier
	ds_read_b128 v[172:175], v168 offset:16384
	ds_read_b128 v[190:193], v168 offset:17408
	ds_read_b128 v[194:197], v168 offset:18432
	ds_read_b128 v[198:201], v168 offset:19456
	ds_read_b128 v[202:205], v168 offset:20480
	ds_read_b128 v[206:209], v168 offset:21504
	ds_read_b128 v[224:227], v168 offset:22528
	ds_read_b128 v[228:231], v168 offset:23552
	global_load_lds_dwordx4 v[250:251], off
	v_lshl_add_u64 v[252:253], s[34:35], 0, v[186:187]
	s_mov_b32 m0, s63
	s_nop 0
	global_load_lds_dwordx4 v[252:253], off
	s_barrier
	s_waitcnt lgkmcnt(0)
	s_setprio 1
	v_mfma_f32_16x16x32_bf16 v[60:63], v[136:139], v[172:175], v[60:63]
	v_mfma_f32_16x16x32_bf16 v[52:55], v[144:147], v[172:175], v[52:55]
	v_mfma_f32_16x16x32_bf16 v[44:47], v[136:139], v[194:197], v[44:47]
	v_mfma_f32_16x16x32_bf16 v[36:39], v[144:147], v[194:197], v[36:39]
	v_mfma_f32_16x16x32_bf16 v[28:31], v[136:139], v[202:205], v[28:31]
	v_mfma_f32_16x16x32_bf16 v[20:23], v[144:147], v[202:205], v[20:23]
	v_mfma_f32_16x16x32_bf16 v[12:15], v[136:139], v[224:227], v[12:15]
	v_mfma_f32_16x16x32_bf16 v[4:7], v[144:147], v[224:227], v[4:7]
	v_mfma_f32_16x16x32_bf16 v[60:63], v[140:143], v[190:193], v[60:63]
	v_mfma_f32_16x16x32_bf16 v[52:55], v[148:151], v[190:193], v[52:55]
	v_mfma_f32_16x16x32_bf16 v[44:47], v[140:143], v[198:201], v[44:47]
	v_mfma_f32_16x16x32_bf16 v[36:39], v[148:151], v[198:201], v[36:39]
	v_mfma_f32_16x16x32_bf16 v[28:31], v[140:143], v[206:209], v[28:31]
	v_mfma_f32_16x16x32_bf16 v[20:23], v[148:151], v[206:209], v[20:23]
	v_mfma_f32_16x16x32_bf16 v[12:15], v[140:143], v[228:231], v[12:15]
	v_mfma_f32_16x16x32_bf16 v[4:7], v[148:151], v[228:231], v[4:7]
	s_setprio 0
	s_barrier
	s_add_u32 s74, s28, 0x80000
	s_addc_u32 s75, s29, 0
	s_add_i32 s3, s85, s61
	v_lshl_add_u64 v[136:137], s[74:75], 0, v[184:185]
	s_mov_b32 m0, s3
	s_nop 0
	global_load_lds_dwordx4 v[136:137], off
	v_lshl_add_u64 v[136:137], s[74:75], 0, v[188:189]
	s_add_i32 m0, s3, 0x2000
	s_nop 0
	global_load_lds_dwordx4 v[136:137], off
	s_waitcnt vmcnt(6)
	s_barrier
	s_setprio 1
	v_mfma_f32_16x16x32_bf16 v[56:59], v[232:235], v[172:175], v[56:59]
	v_mfma_f32_16x16x32_bf16 v[48:51], v[240:243], v[172:175], v[48:51]
	v_mfma_f32_16x16x32_bf16 v[40:43], v[232:235], v[194:197], v[40:43]
	v_mfma_f32_16x16x32_bf16 v[32:35], v[240:243], v[194:197], v[32:35]
	v_mfma_f32_16x16x32_bf16 v[24:27], v[232:235], v[202:205], v[24:27]
	v_mfma_f32_16x16x32_bf16 v[16:19], v[240:243], v[202:205], v[16:19]
	v_mfma_f32_16x16x32_bf16 v[8:11], v[232:235], v[224:227], v[8:11]
	v_mfma_f32_16x16x32_bf16 v[0:3], v[240:243], v[224:227], v[0:3]
	v_mfma_f32_16x16x32_bf16 v[56:59], v[236:239], v[190:193], v[56:59]
	v_mfma_f32_16x16x32_bf16 v[48:51], v[244:247], v[190:193], v[48:51]
	v_mfma_f32_16x16x32_bf16 v[40:43], v[236:239], v[198:201], v[40:43]
	v_mfma_f32_16x16x32_bf16 v[32:35], v[244:247], v[198:201], v[32:35]
	v_mfma_f32_16x16x32_bf16 v[24:27], v[236:239], v[206:209], v[24:27]
	v_mfma_f32_16x16x32_bf16 v[16:19], v[244:247], v[206:209], v[16:19]
	v_mfma_f32_16x16x32_bf16 v[8:11], v[236:239], v[228:231], v[8:11]
	v_mfma_f32_16x16x32_bf16 v[0:3], v[244:247], v[228:231], v[0:3]
	s_setprio 0
	s_add_i32 s3, 0, 0x18000
	v_add_u32_e32 v130, s3, v165
	s_barrier
	ds_read_b128 v[136:139], v130
	ds_read_b128 v[140:143], v130 offset:1024
	ds_read_b128 v[144:147], v130 offset:2048
	ds_read_b128 v[148:151], v130 offset:3072
	s_add_u32 s34, s34, 0x80000
	s_addc_u32 s35, s35, 0
	s_mov_b32 m0, s64
	v_lshl_add_u64 v[232:233], s[34:35], 0, v[182:183]
	ds_read_b128 v[172:175], v168 offset:32768
	ds_read_b128 v[190:193], v168 offset:33792
	ds_read_b128 v[194:197], v168 offset:34816
	ds_read_b128 v[198:201], v168 offset:35840
	ds_read_b128 v[202:205], v168 offset:36864
	ds_read_b128 v[206:209], v168 offset:37888
	ds_read_b128 v[224:227], v168 offset:38912
	ds_read_b128 v[228:231], v168 offset:39936
	global_load_lds_dwordx4 v[232:233], off
	v_lshl_add_u64 v[232:233], s[34:35], 0, v[186:187]
	s_mov_b32 m0, s65
	s_nop 0
	global_load_lds_dwordx4 v[232:233], off
	s_waitcnt lgkmcnt(8)
	s_barrier
	s_waitcnt lgkmcnt(0)
	s_setprio 1
	v_mfma_f32_16x16x32_bf16 v[124:127], v[136:139], v[172:175], v[124:127]
	v_mfma_f32_16x16x32_bf16 v[116:119], v[144:147], v[172:175], v[116:119]
	v_mfma_f32_16x16x32_bf16 v[108:111], v[136:139], v[194:197], v[108:111]
	v_mfma_f32_16x16x32_bf16 v[100:103], v[144:147], v[194:197], v[100:103]
	v_mfma_f32_16x16x32_bf16 v[92:95], v[136:139], v[202:205], v[92:95]
	v_mfma_f32_16x16x32_bf16 v[84:87], v[144:147], v[202:205], v[84:87]
	v_mfma_f32_16x16x32_bf16 v[76:79], v[136:139], v[224:227], v[76:79]
	v_mfma_f32_16x16x32_bf16 v[68:71], v[144:147], v[224:227], v[68:71]
	v_mfma_f32_16x16x32_bf16 v[124:127], v[140:143], v[190:193], v[124:127]
	v_mfma_f32_16x16x32_bf16 v[116:119], v[148:151], v[190:193], v[116:119]
	v_mfma_f32_16x16x32_bf16 v[108:111], v[140:143], v[198:201], v[108:111]
	v_mfma_f32_16x16x32_bf16 v[100:103], v[148:151], v[198:201], v[100:103]
	v_mfma_f32_16x16x32_bf16 v[92:95], v[140:143], v[206:209], v[92:95]
	v_mfma_f32_16x16x32_bf16 v[84:87], v[148:151], v[206:209], v[84:87]
	v_mfma_f32_16x16x32_bf16 v[76:79], v[140:143], v[228:231], v[76:79]
	v_mfma_f32_16x16x32_bf16 v[68:71], v[148:151], v[228:231], v[68:71]
	s_setprio 0
	s_barrier
	s_add_i32 s33, 0, 0x1c000
	s_add_i32 s3, s3, s61
	v_add_u32_e32 v130, s33, v165
	v_lshl_add_u64 v[152:153], v[152:153], 0, s[86:87]
	s_mov_b32 m0, s3
	ds_read_b128 v[232:235], v130
	ds_read_b128 v[236:239], v130 offset:1024
	ds_read_b128 v[240:243], v130 offset:2048
	ds_read_b128 v[244:247], v130 offset:3072
	global_load_lds_dwordx4 v[152:153], off
	v_lshl_add_u64 v[152:153], v[248:249], 0, s[86:87]
	s_add_i32 m0, s3, 0x2000
	s_nop 0
	global_load_lds_dwordx4 v[152:153], off
	s_barrier
	s_waitcnt lgkmcnt(0)
	s_setprio 1
	v_mfma_f32_16x16x32_bf16 v[120:123], v[232:235], v[172:175], v[120:123]
	v_mfma_f32_16x16x32_bf16 v[112:115], v[240:243], v[172:175], v[112:115]
	v_mfma_f32_16x16x32_bf16 v[104:107], v[232:235], v[194:197], v[104:107]
	v_mfma_f32_16x16x32_bf16 v[96:99], v[240:243], v[194:197], v[96:99]
	v_mfma_f32_16x16x32_bf16 v[88:91], v[232:235], v[202:205], v[88:91]
	v_mfma_f32_16x16x32_bf16 v[80:83], v[240:243], v[202:205], v[80:83]
	v_mfma_f32_16x16x32_bf16 v[72:75], v[232:235], v[224:227], v[72:75]
	v_mfma_f32_16x16x32_bf16 v[64:67], v[240:243], v[224:227], v[64:67]
	v_mfma_f32_16x16x32_bf16 v[120:123], v[236:239], v[190:193], v[120:123]
	v_mfma_f32_16x16x32_bf16 v[112:115], v[244:247], v[190:193], v[112:115]
	v_mfma_f32_16x16x32_bf16 v[104:107], v[236:239], v[198:201], v[104:107]
	v_mfma_f32_16x16x32_bf16 v[96:99], v[244:247], v[198:201], v[96:99]
	v_mfma_f32_16x16x32_bf16 v[88:91], v[236:239], v[206:209], v[88:91]
	v_mfma_f32_16x16x32_bf16 v[80:83], v[244:247], v[206:209], v[80:83]
	v_mfma_f32_16x16x32_bf16 v[72:75], v[236:239], v[228:231], v[72:75]
	v_mfma_f32_16x16x32_bf16 v[64:67], v[244:247], v[228:231], v[64:67]
	s_setprio 0
	s_mov_b32 m0, s67
	v_lshl_add_u64 v[152:153], v[250:251], 0, s[86:87]
	s_barrier
	ds_read_b128 v[172:175], v168 offset:49152
	ds_read_b128 v[190:193], v168 offset:50176
	ds_read_b128 v[194:197], v168 offset:51200
	ds_read_b128 v[198:201], v168 offset:52224
	ds_read_b128 v[202:205], v168 offset:53248
	ds_read_b128 v[206:209], v168 offset:54272
	ds_read_b128 v[224:227], v168 offset:55296
	ds_read_b128 v[228:231], v168 offset:56320
	global_load_lds_dwordx4 v[152:153], off
	v_lshl_add_u64 v[152:153], v[252:253], 0, s[86:87]
	s_mov_b32 m0, s68
	s_nop 0
	global_load_lds_dwordx4 v[152:153], off
	s_barrier
	s_waitcnt lgkmcnt(0)
	s_setprio 1
	v_mfma_f32_16x16x32_bf16 v[60:63], v[136:139], v[172:175], v[60:63]
	v_mfma_f32_16x16x32_bf16 v[52:55], v[144:147], v[172:175], v[52:55]
	v_mfma_f32_16x16x32_bf16 v[44:47], v[136:139], v[194:197], v[44:47]
	v_mfma_f32_16x16x32_bf16 v[36:39], v[144:147], v[194:197], v[36:39]
	v_mfma_f32_16x16x32_bf16 v[28:31], v[136:139], v[202:205], v[28:31]
	v_mfma_f32_16x16x32_bf16 v[20:23], v[144:147], v[202:205], v[20:23]
	v_mfma_f32_16x16x32_bf16 v[12:15], v[136:139], v[224:227], v[12:15]
	v_mfma_f32_16x16x32_bf16 v[4:7], v[144:147], v[224:227], v[4:7]
	v_mfma_f32_16x16x32_bf16 v[60:63], v[140:143], v[190:193], v[60:63]
	v_mfma_f32_16x16x32_bf16 v[52:55], v[148:151], v[190:193], v[52:55]
	v_mfma_f32_16x16x32_bf16 v[44:47], v[140:143], v[198:201], v[44:47]
	v_mfma_f32_16x16x32_bf16 v[36:39], v[148:151], v[198:201], v[36:39]
	v_mfma_f32_16x16x32_bf16 v[28:31], v[140:143], v[206:209], v[28:31]
	v_mfma_f32_16x16x32_bf16 v[20:23], v[148:151], v[206:209], v[20:23]
	v_mfma_f32_16x16x32_bf16 v[12:15], v[140:143], v[228:231], v[12:15]
	v_mfma_f32_16x16x32_bf16 v[4:7], v[148:151], v[228:231], v[4:7]
	s_setprio 0
	s_barrier
	s_add_u32 s28, s28, 0x80080
	s_addc_u32 s29, s29, 0
	s_add_i32 s3, s33, s61
	v_lshl_add_u64 v[136:137], s[28:29], 0, v[184:185]
	s_mov_b32 m0, s3
	s_nop 0
	global_load_lds_dwordx4 v[136:137], off
	v_lshl_add_u64 v[136:137], s[28:29], 0, v[188:189]
	s_add_i32 m0, s3, 0x2000
	s_nop 0
	global_load_lds_dwordx4 v[136:137], off
	s_waitcnt vmcnt(6)
	s_barrier
	s_setprio 1
	v_mfma_f32_16x16x32_bf16 v[56:59], v[232:235], v[172:175], v[56:59]
	v_mfma_f32_16x16x32_bf16 v[48:51], v[240:243], v[172:175], v[48:51]
	v_mfma_f32_16x16x32_bf16 v[40:43], v[232:235], v[194:197], v[40:43]
	v_mfma_f32_16x16x32_bf16 v[32:35], v[240:243], v[194:197], v[32:35]
	v_mfma_f32_16x16x32_bf16 v[24:27], v[232:235], v[202:205], v[24:27]
	v_mfma_f32_16x16x32_bf16 v[16:19], v[240:243], v[202:205], v[16:19]
	v_mfma_f32_16x16x32_bf16 v[8:11], v[232:235], v[224:227], v[8:11]
	v_mfma_f32_16x16x32_bf16 v[0:3], v[240:243], v[224:227], v[0:3]
	v_mfma_f32_16x16x32_bf16 v[56:59], v[236:239], v[190:193], v[56:59]
	v_mfma_f32_16x16x32_bf16 v[48:51], v[244:247], v[190:193], v[48:51]
	v_mfma_f32_16x16x32_bf16 v[40:43], v[236:239], v[198:201], v[40:43]
	v_mfma_f32_16x16x32_bf16 v[32:35], v[244:247], v[198:201], v[32:35]
	v_mfma_f32_16x16x32_bf16 v[24:27], v[236:239], v[206:209], v[24:27]
	v_mfma_f32_16x16x32_bf16 v[16:19], v[244:247], v[206:209], v[16:19]
	v_mfma_f32_16x16x32_bf16 v[8:11], v[236:239], v[228:231], v[8:11]
	v_mfma_f32_16x16x32_bf16 v[0:3], v[244:247], v[228:231], v[0:3]
	s_setprio 0
	s_add_i32 vcc_lo, vcc_lo, 2
	s_add_u32 s10, s10, 0x100
	s_addc_u32 s11, s11, 0
	s_add_u32 s93, s93, 0x100
	s_addc_u32 s95, s95, 0
	s_cmp_gt_u32 vcc_lo, 29
	s_barrier
	s_cbranch_scc0 .LBB0_234
	v_lshl_add_u32 v136, s8, 8, v129
	s_cmp_gt_i32 s92, 15
	s_mov_b64 s[8:9], -1
	s_cbranch_scc0 .LBB0_285
	s_lshr_b32 s3, s92, 3
	s_add_i32 s3, s3, -2
	s_cmp_eq_u32 s3, 0
	s_cselect_b64 s[8:9], -1, 0
	v_mov_b32_e32 v130, 0xbfb8aa3b
	v_mov_b32_e32 v137, 0xc0135761
	s_cmp_eq_u32 s3, 1
	v_cndmask_b32_e64 v138, v130, v137, s[8:9]
	s_cselect_b64 s[28:29], -1, 0
	s_cmp_lg_u32 s3, 1
	v_cndmask_b32_e64 v140, 0, v170, s[8:9]
	s_cselect_b64 s[10:11], -1, 0
	v_mov_b32_e32 v141, v140
	v_mov_b32_e32 v139, v138
	s_and_b64 vcc, exec, s[28:29]
	s_cbranch_vccnz .LBB0_238
	v_pk_mul_f32 v[142:143], v[126:127], v[126:127]
	v_pk_mul_f32 v[144:145], v[124:125], v[124:125]
	v_pk_mul_f32 v[146:147], v[118:119], v[118:119]
	v_pk_mul_f32 v[148:149], v[116:117], v[116:117]
	v_pk_fma_f32 v[144:145], v[140:141], v[144:145], v[138:139]
	v_pk_fma_f32 v[142:143], v[140:141], v[142:143], v[138:139]
	v_pk_fma_f32 v[148:149], v[140:141], v[148:149], v[138:139]
	v_pk_fma_f32 v[146:147], v[140:141], v[146:147], v[138:139]
	v_pk_mul_f32 v[144:145], v[124:125], v[144:145]
	v_pk_mul_f32 v[142:143], v[126:127], v[142:143]
	v_pk_mul_f32 v[148:149], v[116:117], v[148:149]
	v_pk_mul_f32 v[146:147], v[118:119], v[146:147]
	v_exp_f32_e32 v144, v144
	v_exp_f32_e32 v145, v145
	v_exp_f32_e32 v142, v142
	v_exp_f32_e32 v143, v143
	v_exp_f32_e32 v148, v148
	v_exp_f32_e32 v149, v149
	v_exp_f32_e32 v146, v146
	v_exp_f32_e32 v147, v147
	v_pk_add_f32 v[144:145], v[144:145], 1.0 op_sel_hi:[1,0]
	v_pk_add_f32 v[142:143], v[142:143], 1.0 op_sel_hi:[1,0]
	v_pk_add_f32 v[148:149], v[148:149], 1.0 op_sel_hi:[1,0]
	v_pk_add_f32 v[146:147], v[146:147], 1.0 op_sel_hi:[1,0]
	v_rcp_f32_e32 v144, v144
	v_rcp_f32_e32 v145, v145
	v_rcp_f32_e32 v142, v142
	v_rcp_f32_e32 v143, v143
	v_rcp_f32_e32 v152, v148
	v_rcp_f32_e32 v153, v149
	v_rcp_f32_e32 v150, v146
	v_rcp_f32_e32 v151, v147
	v_pk_mul_f32 v[146:147], v[126:127], v[142:143]
	v_pk_mul_f32 v[148:149], v[124:125], v[144:145]
	v_pk_mul_f32 v[152:153], v[116:117], v[152:153]
	v_pk_mul_f32 v[150:151], v[118:119], v[150:151]
	s_branch .LBB0_239

.LBB0_558:
	ds_read_b128 v[40:43], v228
	ds_read_b128 v[44:47], v228 offset:1024
	ds_read_b128 v[52:55], v228 offset:2048
	ds_read_b128 v[60:63], v228 offset:3072
	s_add_u32 s3, s10, 0xfff80080
	s_addc_u32 s28, s11, -1
	s_cmp_eq_u32 s84, s86
	s_cselect_b32 s35, s41, s28
	s_cselect_b32 s34, s43, s3
	s_cselect_b32 s29, s39, s85
	s_cselect_b32 s28, s50, s51
	v_lshl_add_u64 v[198:199], s[10:11], 0, v[192:193]
	s_add_i32 m0, s61, 0xc000
	ds_read_b128 v[144:147], v229
	ds_read_b128 v[148:151], v229 offset:1024
	ds_read_b128 v[152:155], v229 offset:2048
	ds_read_b128 v[156:159], v229 offset:3072
	ds_read_b128 v[160:163], v229 offset:4096
	ds_read_b128 v[164:167], v229 offset:5120
	ds_read_b128 v[168:171], v229 offset:6144
	ds_read_b128 v[172:175], v229 offset:7168
	global_load_lds_dwordx4 v[198:199], off
	v_lshl_add_u64 v[198:199], s[10:11], 0, v[194:195]
	s_add_i32 m0, s61, 0xe000
	s_nop 0
	global_load_lds_dwordx4 v[198:199], off
	s_waitcnt lgkmcnt(8)
	s_barrier
	s_waitcnt lgkmcnt(0)
	s_setprio 1
	v_mfma_f32_16x16x32_bf16 v[140:143], v[40:43], v[144:147], v[140:143]
	v_mfma_f32_16x16x32_bf16 v[136:139], v[52:55], v[144:147], v[136:139]
	v_mfma_f32_16x16x32_bf16 v[124:127], v[40:43], v[152:155], v[124:127]
	v_mfma_f32_16x16x32_bf16 v[120:123], v[52:55], v[152:155], v[120:123]
	v_mfma_f32_16x16x32_bf16 v[108:111], v[40:43], v[160:163], v[108:111]
	v_mfma_f32_16x16x32_bf16 v[104:107], v[52:55], v[160:163], v[104:107]
	v_mfma_f32_16x16x32_bf16 v[92:95], v[40:43], v[168:171], v[92:95]
	v_mfma_f32_16x16x32_bf16 v[88:91], v[52:55], v[168:171], v[88:91]
	v_mfma_f32_16x16x32_bf16 v[140:143], v[44:47], v[148:151], v[140:143]
	v_mfma_f32_16x16x32_bf16 v[136:139], v[60:63], v[148:151], v[136:139]
	v_mfma_f32_16x16x32_bf16 v[124:127], v[44:47], v[156:159], v[124:127]
	v_mfma_f32_16x16x32_bf16 v[120:123], v[60:63], v[156:159], v[120:123]
	v_mfma_f32_16x16x32_bf16 v[108:111], v[44:47], v[164:167], v[108:111]
	v_mfma_f32_16x16x32_bf16 v[104:107], v[60:63], v[164:167], v[104:107]
	v_mfma_f32_16x16x32_bf16 v[92:95], v[44:47], v[172:175], v[92:95]
	v_mfma_f32_16x16x32_bf16 v[88:91], v[60:63], v[172:175], v[88:91]
	s_setprio 0
	s_barrier
	s_add_i32 s3, s79, s69
	v_lshl_add_u64 v[236:237], s[28:29], 0, v[184:185]
	s_mov_b32 m0, s3
	ds_read_b128 v[198:201], v230
	ds_read_b128 v[202:205], v230 offset:1024
	ds_read_b128 v[206:209], v230 offset:2048
	ds_read_b128 v[232:235], v230 offset:3072
	global_load_lds_dwordx4 v[236:237], off
	v_lshl_add_u64 v[238:239], s[28:29], 0, v[188:189]
	s_add_i32 m0, s3, 0x2000
	s_nop 0
	global_load_lds_dwordx4 v[238:239], off
	s_barrier
	s_waitcnt lgkmcnt(0)
	s_setprio 1
	v_mfma_f32_16x16x32_bf16 v[132:135], v[198:201], v[144:147], v[132:135]
	v_mfma_f32_16x16x32_bf16 v[128:131], v[206:209], v[144:147], v[128:131]
	v_mfma_f32_16x16x32_bf16 v[116:119], v[198:201], v[152:155], v[116:119]
	v_mfma_f32_16x16x32_bf16 v[112:115], v[206:209], v[152:155], v[112:115]
	v_mfma_f32_16x16x32_bf16 v[100:103], v[198:201], v[160:163], v[100:103]
	v_mfma_f32_16x16x32_bf16 v[96:99], v[206:209], v[160:163], v[96:99]
	v_mfma_f32_16x16x32_bf16 v[84:87], v[198:201], v[168:171], v[84:87]
	v_mfma_f32_16x16x32_bf16 v[80:83], v[206:209], v[168:171], v[80:83]
	v_mfma_f32_16x16x32_bf16 v[132:135], v[202:205], v[148:151], v[132:135]
	v_mfma_f32_16x16x32_bf16 v[128:131], v[232:235], v[148:151], v[128:131]
	v_mfma_f32_16x16x32_bf16 v[116:119], v[202:205], v[156:159], v[116:119]
	v_mfma_f32_16x16x32_bf16 v[112:115], v[232:235], v[156:159], v[112:115]
	v_mfma_f32_16x16x32_bf16 v[100:103], v[202:205], v[164:167], v[100:103]
	v_mfma_f32_16x16x32_bf16 v[96:99], v[232:235], v[164:167], v[96:99]
	v_mfma_f32_16x16x32_bf16 v[84:87], v[202:205], v[172:175], v[84:87]
	v_mfma_f32_16x16x32_bf16 v[80:83], v[232:235], v[172:175], v[80:83]
	s_setprio 0
	s_mov_b32 m0, s61
	v_lshl_add_u64 v[240:241], s[34:35], 0, v[182:183]
	s_barrier
	ds_read_b128 v[144:147], v229 offset:16384
	ds_read_b128 v[148:151], v229 offset:17408
	ds_read_b128 v[152:155], v229 offset:18432
	ds_read_b128 v[156:159], v229 offset:19456
	ds_read_b128 v[160:163], v229 offset:20480
	ds_read_b128 v[164:167], v229 offset:21504
	ds_read_b128 v[168:171], v229 offset:22528
	ds_read_b128 v[172:175], v229 offset:23552
	global_load_lds_dwordx4 v[240:241], off
	v_lshl_add_u64 v[242:243], s[34:35], 0, v[186:187]
	s_mov_b32 m0, s63
	s_nop 0
	global_load_lds_dwordx4 v[242:243], off
	s_barrier
	s_waitcnt lgkmcnt(0)
	s_setprio 1
	v_mfma_f32_16x16x32_bf16 v[76:79], v[40:43], v[144:147], v[76:79]
	v_mfma_f32_16x16x32_bf16 v[72:75], v[52:55], v[144:147], v[72:75]
	v_mfma_f32_16x16x32_bf16 v[56:59], v[40:43], v[152:155], v[56:59]
	v_mfma_f32_16x16x32_bf16 v[48:51], v[52:55], v[152:155], v[48:51]
	v_mfma_f32_16x16x32_bf16 v[28:31], v[40:43], v[160:163], v[28:31]
	v_mfma_f32_16x16x32_bf16 v[24:27], v[52:55], v[160:163], v[24:27]
	v_mfma_f32_16x16x32_bf16 v[12:15], v[40:43], v[168:171], v[12:15]
	v_mfma_f32_16x16x32_bf16 v[8:11], v[52:55], v[168:171], v[8:11]
	v_mfma_f32_16x16x32_bf16 v[76:79], v[44:47], v[148:151], v[76:79]
	v_mfma_f32_16x16x32_bf16 v[72:75], v[60:63], v[148:151], v[72:75]
	v_mfma_f32_16x16x32_bf16 v[56:59], v[44:47], v[156:159], v[56:59]
	v_mfma_f32_16x16x32_bf16 v[48:51], v[60:63], v[156:159], v[48:51]
	v_mfma_f32_16x16x32_bf16 v[28:31], v[44:47], v[164:167], v[28:31]
	v_mfma_f32_16x16x32_bf16 v[24:27], v[60:63], v[164:167], v[24:27]
	v_mfma_f32_16x16x32_bf16 v[12:15], v[44:47], v[172:175], v[12:15]
	v_mfma_f32_16x16x32_bf16 v[8:11], v[60:63], v[172:175], v[8:11]
	s_setprio 0
	s_barrier
	s_add_u32 s88, s28, 0x80000
	s_addc_u32 s89, s29, 0
	s_add_i32 s3, s80, s69
	v_lshl_add_u64 v[40:41], s[88:89], 0, v[184:185]
	s_mov_b32 m0, s3
	s_nop 0
	global_load_lds_dwordx4 v[40:41], off
	v_lshl_add_u64 v[40:41], s[88:89], 0, v[188:189]
	s_add_i32 m0, s3, 0x2000
	s_nop 0
	global_load_lds_dwordx4 v[40:41], off
	s_waitcnt vmcnt(6)
	s_barrier
	s_setprio 1
	v_mfma_f32_16x16x32_bf16 v[36:39], v[198:201], v[152:155], v[36:39]
	v_mfma_f32_16x16x32_bf16 v[32:35], v[206:209], v[152:155], v[32:35]
	v_mfma_f32_16x16x32_bf16 v[20:23], v[198:201], v[160:163], v[20:23]
	v_mfma_f32_16x16x32_bf16 v[16:19], v[206:209], v[160:163], v[16:19]
	v_mfma_f32_16x16x32_bf16 v[4:7], v[198:201], v[168:171], v[4:7]
	v_mfma_f32_16x16x32_bf16 v[0:3], v[206:209], v[168:171], v[0:3]
	v_mfma_f32_16x16x32_bf16 v[40:43], v[198:201], v[144:147], v[68:71]
	v_mfma_f32_16x16x32_bf16 v[44:47], v[206:209], v[144:147], v[64:67]
	v_mfma_f32_16x16x32_bf16 v[36:39], v[202:205], v[156:159], v[36:39]
	v_mfma_f32_16x16x32_bf16 v[32:35], v[232:235], v[156:159], v[32:35]
	v_mfma_f32_16x16x32_bf16 v[20:23], v[202:205], v[164:167], v[20:23]
	v_mfma_f32_16x16x32_bf16 v[16:19], v[232:235], v[164:167], v[16:19]
	v_mfma_f32_16x16x32_bf16 v[4:7], v[202:205], v[172:175], v[4:7]
	v_mfma_f32_16x16x32_bf16 v[0:3], v[232:235], v[172:175], v[0:3]
	v_mfma_f32_16x16x32_bf16 v[40:43], v[202:205], v[148:151], v[40:43]
	v_mfma_f32_16x16x32_bf16 v[44:47], v[232:235], v[148:151], v[44:47]
	s_setprio 0
	s_add_i32 s3, 0, 0x18000
	v_add_u32_e32 v68, s3, v226
	s_barrier
	ds_read_b128 v[52:55], v68
	ds_read_b128 v[60:63], v68 offset:1024
	ds_read_b128 v[64:67], v68 offset:2048
	ds_read_b128 v[68:71], v68 offset:3072
	s_add_u32 s34, s34, 0x80000
	s_addc_u32 s35, s35, 0
	s_mov_b32 m0, s67
	v_lshl_add_u64 v[198:199], s[34:35], 0, v[182:183]
	ds_read_b128 v[144:147], v229 offset:32768
	ds_read_b128 v[148:151], v229 offset:33792
	ds_read_b128 v[152:155], v229 offset:34816
	ds_read_b128 v[156:159], v229 offset:35840
	ds_read_b128 v[160:163], v229 offset:36864
	ds_read_b128 v[164:167], v229 offset:37888
	ds_read_b128 v[168:171], v229 offset:38912
	ds_read_b128 v[172:175], v229 offset:39936
	global_load_lds_dwordx4 v[198:199], off
	v_lshl_add_u64 v[198:199], s[34:35], 0, v[186:187]
	s_mov_b32 m0, s70
	s_nop 0
	global_load_lds_dwordx4 v[198:199], off
	s_waitcnt lgkmcnt(8)
	s_barrier
	s_waitcnt lgkmcnt(0)
	s_setprio 1
	v_mfma_f32_16x16x32_bf16 v[140:143], v[52:55], v[144:147], v[140:143]
	v_mfma_f32_16x16x32_bf16 v[136:139], v[64:67], v[144:147], v[136:139]
	v_mfma_f32_16x16x32_bf16 v[124:127], v[52:55], v[152:155], v[124:127]
	v_mfma_f32_16x16x32_bf16 v[120:123], v[64:67], v[152:155], v[120:123]
	v_mfma_f32_16x16x32_bf16 v[108:111], v[52:55], v[160:163], v[108:111]
	v_mfma_f32_16x16x32_bf16 v[104:107], v[64:67], v[160:163], v[104:107]
	v_mfma_f32_16x16x32_bf16 v[92:95], v[52:55], v[168:171], v[92:95]
	v_mfma_f32_16x16x32_bf16 v[88:91], v[64:67], v[168:171], v[88:91]
	v_mfma_f32_16x16x32_bf16 v[140:143], v[60:63], v[148:151], v[140:143]
	v_mfma_f32_16x16x32_bf16 v[136:139], v[68:71], v[148:151], v[136:139]
	v_mfma_f32_16x16x32_bf16 v[124:127], v[60:63], v[156:159], v[124:127]
	v_mfma_f32_16x16x32_bf16 v[120:123], v[68:71], v[156:159], v[120:123]
	v_mfma_f32_16x16x32_bf16 v[108:111], v[60:63], v[164:167], v[108:111]
	v_mfma_f32_16x16x32_bf16 v[104:107], v[68:71], v[164:167], v[104:107]
	v_mfma_f32_16x16x32_bf16 v[92:95], v[60:63], v[172:175], v[92:95]
	v_mfma_f32_16x16x32_bf16 v[88:91], v[68:71], v[172:175], v[88:91]
	s_setprio 0
	s_barrier
	s_add_i32 s34, 0, 0x1c000
	s_add_i32 s3, s3, s69
	v_add_u32_e32 v231, s34, v226
	v_lshl_add_u64 v[236:237], v[236:237], 0, s[22:23]
	s_mov_b32 m0, s3
	ds_read_b128 v[198:201], v231
	ds_read_b128 v[202:205], v231 offset:1024
	ds_read_b128 v[206:209], v231 offset:2048
	ds_read_b128 v[232:235], v231 offset:3072
	global_load_lds_dwordx4 v[236:237], off
	v_lshl_add_u64 v[236:237], v[238:239], 0, s[22:23]
	s_add_i32 m0, s3, 0x2000
	s_nop 0
	global_load_lds_dwordx4 v[236:237], off
	s_barrier
	s_waitcnt lgkmcnt(0)
	s_setprio 1
	v_mfma_f32_16x16x32_bf16 v[132:135], v[198:201], v[144:147], v[132:135]
	v_mfma_f32_16x16x32_bf16 v[128:131], v[206:209], v[144:147], v[128:131]
	v_mfma_f32_16x16x32_bf16 v[116:119], v[198:201], v[152:155], v[116:119]
	v_mfma_f32_16x16x32_bf16 v[112:115], v[206:209], v[152:155], v[112:115]
	v_mfma_f32_16x16x32_bf16 v[100:103], v[198:201], v[160:163], v[100:103]
	v_mfma_f32_16x16x32_bf16 v[96:99], v[206:209], v[160:163], v[96:99]
	v_mfma_f32_16x16x32_bf16 v[84:87], v[198:201], v[168:171], v[84:87]
	v_mfma_f32_16x16x32_bf16 v[80:83], v[206:209], v[168:171], v[80:83]
	v_mfma_f32_16x16x32_bf16 v[132:135], v[202:205], v[148:151], v[132:135]
	v_mfma_f32_16x16x32_bf16 v[128:131], v[232:235], v[148:151], v[128:131]
	v_mfma_f32_16x16x32_bf16 v[116:119], v[202:205], v[156:159], v[116:119]
	v_mfma_f32_16x16x32_bf16 v[112:115], v[232:235], v[156:159], v[112:115]
	v_mfma_f32_16x16x32_bf16 v[100:103], v[202:205], v[164:167], v[100:103]
	v_mfma_f32_16x16x32_bf16 v[96:99], v[232:235], v[164:167], v[96:99]
	v_mfma_f32_16x16x32_bf16 v[84:87], v[202:205], v[172:175], v[84:87]
	v_mfma_f32_16x16x32_bf16 v[80:83], v[232:235], v[172:175], v[80:83]
	s_setprio 0
	s_mov_b32 m0, s71
	v_lshl_add_u64 v[236:237], v[240:241], 0, s[22:23]
	s_barrier
	ds_read_b128 v[144:147], v229 offset:49152
	ds_read_b128 v[148:151], v229 offset:50176
	ds_read_b128 v[152:155], v229 offset:51200
	ds_read_b128 v[156:159], v229 offset:52224
	ds_read_b128 v[160:163], v229 offset:53248
	ds_read_b128 v[164:167], v229 offset:54272
	ds_read_b128 v[168:171], v229 offset:55296
	ds_read_b128 v[172:175], v229 offset:56320
	global_load_lds_dwordx4 v[236:237], off
	v_lshl_add_u64 v[236:237], v[242:243], 0, s[22:23]
	s_mov_b32 m0, s74
	s_nop 0
	global_load_lds_dwordx4 v[236:237], off
	s_barrier
	s_waitcnt lgkmcnt(0)
	s_setprio 1
	v_mfma_f32_16x16x32_bf16 v[76:79], v[52:55], v[144:147], v[76:79]
	v_mfma_f32_16x16x32_bf16 v[72:75], v[64:67], v[144:147], v[72:75]
	v_mfma_f32_16x16x32_bf16 v[56:59], v[52:55], v[152:155], v[56:59]
	v_mfma_f32_16x16x32_bf16 v[48:51], v[64:67], v[152:155], v[48:51]
	v_mfma_f32_16x16x32_bf16 v[28:31], v[52:55], v[160:163], v[28:31]
	v_mfma_f32_16x16x32_bf16 v[24:27], v[64:67], v[160:163], v[24:27]
	v_mfma_f32_16x16x32_bf16 v[12:15], v[52:55], v[168:171], v[12:15]
	v_mfma_f32_16x16x32_bf16 v[8:11], v[64:67], v[168:171], v[8:11]
	v_mfma_f32_16x16x32_bf16 v[76:79], v[60:63], v[148:151], v[76:79]
	v_mfma_f32_16x16x32_bf16 v[72:75], v[68:71], v[148:151], v[72:75]
	v_mfma_f32_16x16x32_bf16 v[56:59], v[60:63], v[156:159], v[56:59]
	v_mfma_f32_16x16x32_bf16 v[48:51], v[68:71], v[156:159], v[48:51]
	v_mfma_f32_16x16x32_bf16 v[28:31], v[60:63], v[164:167], v[28:31]
	v_mfma_f32_16x16x32_bf16 v[24:27], v[68:71], v[164:167], v[24:27]
	v_mfma_f32_16x16x32_bf16 v[12:15], v[60:63], v[172:175], v[12:15]
	v_mfma_f32_16x16x32_bf16 v[8:11], v[68:71], v[172:175], v[8:11]
	s_setprio 0
	s_barrier
	s_add_u32 s28, s28, 0x80080
	s_addc_u32 s29, s29, 0
	s_add_i32 s3, s34, s69
	v_lshl_add_u64 v[52:53], s[28:29], 0, v[184:185]
	s_mov_b32 m0, s3
	s_nop 0
	global_load_lds_dwordx4 v[52:53], off
	v_lshl_add_u64 v[52:53], s[28:29], 0, v[188:189]
	s_add_i32 m0, s3, 0x2000
	s_nop 0
	global_load_lds_dwordx4 v[52:53], off
	s_waitcnt vmcnt(6)
	s_barrier
	s_setprio 1
	v_mfma_f32_16x16x32_bf16 v[40:43], v[198:201], v[144:147], v[40:43]
	v_mfma_f32_16x16x32_bf16 v[68:71], v[202:205], v[148:151], v[40:43]
	v_mfma_f32_16x16x32_bf16 v[40:43], v[206:209], v[144:147], v[44:47]
	v_mfma_f32_16x16x32_bf16 v[36:39], v[198:201], v[152:155], v[36:39]
	v_mfma_f32_16x16x32_bf16 v[32:35], v[206:209], v[152:155], v[32:35]
	v_mfma_f32_16x16x32_bf16 v[20:23], v[198:201], v[160:163], v[20:23]
	v_mfma_f32_16x16x32_bf16 v[16:19], v[206:209], v[160:163], v[16:19]
	v_mfma_f32_16x16x32_bf16 v[4:7], v[198:201], v[168:171], v[4:7]
	v_mfma_f32_16x16x32_bf16 v[0:3], v[206:209], v[168:171], v[0:3]
	v_mfma_f32_16x16x32_bf16 v[64:67], v[232:235], v[148:151], v[40:43]
	v_mfma_f32_16x16x32_bf16 v[36:39], v[202:205], v[156:159], v[36:39]
	v_mfma_f32_16x16x32_bf16 v[32:35], v[232:235], v[156:159], v[32:35]
	v_mfma_f32_16x16x32_bf16 v[20:23], v[202:205], v[164:167], v[20:23]
	v_mfma_f32_16x16x32_bf16 v[16:19], v[232:235], v[164:167], v[16:19]
	v_mfma_f32_16x16x32_bf16 v[4:7], v[202:205], v[172:175], v[4:7]
	v_mfma_f32_16x16x32_bf16 v[0:3], v[232:235], v[172:175], v[0:3]
	s_setprio 0
	s_add_i32 s3, s86, 2
	s_add_u32 s10, s10, 0x100
	s_addc_u32 s11, s11, 0
	s_add_u32 s51, s51, 0x100
	s_addc_u32 s85, s85, 0
	s_cmp_ge_u32 s86, s84
	s_mov_b32 s86, s3
	s_barrier
	s_cbranch_scc0 .LBB0_558
	s_cmp_eq_u32 s84, 32
	s_cselect_b64 s[50:51], -1, 0
	s_mov_b64 s[10:11], -1
	s_and_b64 vcc, exec, s[50:51]
	s_cbranch_vccnz .LBB0_562
	s_lshl_b32 s3, s84, 6
	s_sext_i32_i16 s3, s3
	v_cvt_f32_i32_e32 v40, s3
	v_cvt_f32_i32_e32 v41, s66
	s_xor_b32 s3, s66, s3
	s_ashr_i32 s3, s3, 30
	v_rcp_iflag_f32_e32 v43, v40
	s_or_b32 s3, s3, 1
	v_cvt_pk_bf16_f32 v42, v140, v141
	v_cvt_pk_bf16_f32 v44, v136, v137
	v_mul_f32_e32 v43, v41, v43
	v_trunc_f32_e32 v43, v43
	v_fma_f32 v41, -v43, v40, v41
	v_cvt_i32_f32_e32 v43, v43
	v_cmp_ge_f32_e64 s[10:11], |v41|, |v40|
	s_and_b64 s[10:11], s[10:11], exec
	s_cselect_b32 s3, s3, 0
	v_add_u32_e32 v40, s3, v43
	v_bfe_i32 v40, v40, 0, 16
	v_ashrrev_i32_e32 v41, 31, v40
	v_lshlrev_b64 v[40:41], 22, v[40:41]
	v_lshl_add_u64 v[40:41], v[190:191], 0, v[40:41]
	v_cvt_pk_bf16_f32 v43, v142, v143
	v_cvt_pk_bf16_f32 v45, v138, v139
	s_mov_b64 s[10:11], 0x400
	global_store_dwordx4 v[40:41], v[42:45], off sc1
	s_nop 2
	v_cvt_pk_bf16_f32 v42, v132, v133
	v_cvt_pk_bf16_f32 v43, v134, v135
	v_cvt_pk_bf16_f32 v44, v128, v129
	v_cvt_pk_bf16_f32 v45, v130, v131
	v_lshl_add_u64 v[46:47], v[40:41], 0, s[10:11]
	global_store_dwordx4 v[46:47], v[42:45], off sc1
	s_nop 2
	s_mov_b64 s[10:11], 0x800
	v_cvt_pk_bf16_f32 v42, v124, v125
	v_cvt_pk_bf16_f32 v43, v126, v127
	v_cvt_pk_bf16_f32 v44, v120, v121
	v_cvt_pk_bf16_f32 v45, v122, v123
	v_lshl_add_u64 v[46:47], v[40:41], 0, s[10:11]
	global_store_dwordx4 v[46:47], v[42:45], off sc1
	s_nop 2
	s_mov_b64 s[10:11], 0xc00
	v_cvt_pk_bf16_f32 v42, v116, v117
	v_cvt_pk_bf16_f32 v43, v118, v119
	v_cvt_pk_bf16_f32 v44, v112, v113
	v_cvt_pk_bf16_f32 v45, v114, v115
	v_lshl_add_u64 v[46:47], v[40:41], 0, s[10:11]
	global_store_dwordx4 v[46:47], v[42:45], off sc1
	s_nop 2
	s_mov_b64 s[10:11], 0x1000
	v_cvt_pk_bf16_f32 v42, v108, v109
	v_cvt_pk_bf16_f32 v43, v110, v111
	v_cvt_pk_bf16_f32 v44, v104, v105
	v_cvt_pk_bf16_f32 v45, v106, v107
	v_lshl_add_u64 v[46:47], v[40:41], 0, s[10:11]
	global_store_dwordx4 v[46:47], v[42:45], off sc1
	s_nop 2
	s_mov_b64 s[10:11], 0x1400
	v_cvt_pk_bf16_f32 v42, v100, v101
	v_cvt_pk_bf16_f32 v43, v102, v103
	v_cvt_pk_bf16_f32 v44, v96, v97
	v_cvt_pk_bf16_f32 v45, v98, v99
	v_lshl_add_u64 v[46:47], v[40:41], 0, s[10:11]
	global_store_dwordx4 v[46:47], v[42:45], off sc1
	s_nop 2
	s_mov_b64 s[10:11], 0x1800
	v_cvt_pk_bf16_f32 v42, v92, v93
	v_cvt_pk_bf16_f32 v43, v94, v95
	v_cvt_pk_bf16_f32 v44, v88, v89
	v_cvt_pk_bf16_f32 v45, v90, v91
	v_lshl_add_u64 v[46:47], v[40:41], 0, s[10:11]
	global_store_dwordx4 v[46:47], v[42:45], off sc1
	s_nop 2
	s_mov_b64 s[10:11], 0x1c00
	v_cvt_pk_bf16_f32 v42, v84, v85
	v_cvt_pk_bf16_f32 v43, v86, v87
	v_cvt_pk_bf16_f32 v44, v80, v81
	v_cvt_pk_bf16_f32 v45, v82, v83
	v_lshl_add_u64 v[46:47], v[40:41], 0, s[10:11]
	global_store_dwordx4 v[46:47], v[42:45], off sc1
	s_nop 2
	s_mov_b64 s[10:11], 0x2000
	v_cvt_pk_bf16_f32 v42, v76, v77
	v_cvt_pk_bf16_f32 v43, v78, v79
	v_cvt_pk_bf16_f32 v44, v72, v73
	v_cvt_pk_bf16_f32 v45, v74, v75
	v_lshl_add_u64 v[46:47], v[40:41], 0, s[10:11]
	global_store_dwordx4 v[46:47], v[42:45], off sc1
	s_nop 2
	s_mov_b64 s[10:11], 0x2400
	v_cvt_pk_bf16_f32 v42, v68, v69
	v_cvt_pk_bf16_f32 v43, v70, v71
	v_cvt_pk_bf16_f32 v44, v64, v65
	v_cvt_pk_bf16_f32 v45, v66, v67
	v_lshl_add_u64 v[46:47], v[40:41], 0, s[10:11]
	global_store_dwordx4 v[46:47], v[42:45], off sc1
	s_nop 2
	s_mov_b64 s[10:11], 0x2800
	v_cvt_pk_bf16_f32 v42, v56, v57
	v_cvt_pk_bf16_f32 v43, v58, v59
	v_cvt_pk_bf16_f32 v44, v48, v49
	v_cvt_pk_bf16_f32 v45, v50, v51
	v_lshl_add_u64 v[46:47], v[40:41], 0, s[10:11]
	global_store_dwordx4 v[46:47], v[42:45], off sc1
	s_nop 2
	s_mov_b64 s[10:11], 0x2c00
	v_cvt_pk_bf16_f32 v42, v36, v37
	v_cvt_pk_bf16_f32 v43, v38, v39
	v_cvt_pk_bf16_f32 v44, v32, v33
	v_cvt_pk_bf16_f32 v45, v34, v35
	v_lshl_add_u64 v[46:47], v[40:41], 0, s[10:11]
	global_store_dwordx4 v[46:47], v[42:45], off sc1
	s_nop 2
	s_mov_b64 s[10:11], 0x3000
	v_cvt_pk_bf16_f32 v42, v28, v29
	v_cvt_pk_bf16_f32 v43, v30, v31
	v_cvt_pk_bf16_f32 v44, v24, v25
	v_cvt_pk_bf16_f32 v45, v26, v27
	v_lshl_add_u64 v[46:47], v[40:41], 0, s[10:11]
	global_store_dwordx4 v[46:47], v[42:45], off sc1
	s_nop 2
	s_mov_b64 s[10:11], 0x3400
	v_cvt_pk_bf16_f32 v42, v20, v21
	v_cvt_pk_bf16_f32 v43, v22, v23
	v_cvt_pk_bf16_f32 v44, v16, v17
	v_cvt_pk_bf16_f32 v45, v18, v19
	v_lshl_add_u64 v[46:47], v[40:41], 0, s[10:11]
	global_store_dwordx4 v[46:47], v[42:45], off sc1
	s_nop 2
	s_mov_b64 s[10:11], 0x3800
	v_cvt_pk_bf16_f32 v42, v12, v13
	v_cvt_pk_bf16_f32 v43, v14, v15
	v_cvt_pk_bf16_f32 v44, v8, v9
	v_cvt_pk_bf16_f32 v45, v10, v11
	v_lshl_add_u64 v[46:47], v[40:41], 0, s[10:11]
	global_store_dwordx4 v[46:47], v[42:45], off sc1
	s_nop 2
	v_cvt_pk_bf16_f32 v42, v4, v5
	v_cvt_pk_bf16_f32 v43, v6, v7
	v_cvt_pk_bf16_f32 v44, v0, v1
	v_cvt_pk_bf16_f32 v45, v2, v3
	v_lshl_add_u64 v[40:41], v[40:41], 0, s[26:27]
	global_store_dwordx4 v[40:41], v[42:45], off sc1
	s_nop 2
	s_cbranch_execz .LBB0_563

.LBB0_640:
	s_add_i32 s89, s89, 2
	v_add_u32_e32 v56, s71, v139
	s_add_u32 s3, s22, s34
	ds_read_b128 v[150:153], v56
	ds_read_b128 v[154:157], v56 offset:1024
	ds_read_b128 v[158:161], v56 offset:2048
	ds_read_b128 v[162:165], v56 offset:3072
	s_addc_u32 s36, s23, s35
	s_add_u32 s3, s3, 0x100
	s_addc_u32 s36, s36, 0
	s_add_u32 s90, s83, s34
	s_addc_u32 s37, s84, s35
	s_cmp_eq_u32 s88, s34
	s_cselect_b32 s39, s11, s36
	s_cselect_b32 s38, s85, s3
	s_cselect_b32 s37, s86, s37
	s_cselect_b32 s36, s87, s90
	s_mov_b32 m0, s73
	v_lshl_add_u64 v[174:175], v[58:59], 0, s[34:35]
	ds_read_b128 v[166:169], v133
	ds_read_b128 v[170:173], v133 offset:1024
	ds_read_b128 v[182:185], v133 offset:2048
	ds_read_b128 v[186:189], v133 offset:3072
	ds_read_b128 v[190:193], v133 offset:4096
	ds_read_b128 v[194:197], v133 offset:5120
	ds_read_b128 v[198:201], v133 offset:6144
	ds_read_b128 v[202:205], v133 offset:7168
	global_load_lds_dwordx4 v[174:175], off
	v_lshl_add_u64 v[174:175], v[146:147], 0, s[34:35]
	s_mov_b32 m0, s74
	s_nop 0
	global_load_lds_dwordx4 v[174:175], off
	s_waitcnt lgkmcnt(8)
	s_barrier
	s_waitcnt lgkmcnt(0)
	s_setprio 1
	v_mfma_f32_16x16x32_bf16 v[128:131], v[150:153], v[166:169], v[128:131]
	v_mfma_f32_16x16x32_bf16 v[124:127], v[158:161], v[166:169], v[124:127]
	v_mfma_f32_16x16x32_bf16 v[112:115], v[150:153], v[182:185], v[112:115]
	v_mfma_f32_16x16x32_bf16 v[108:111], v[158:161], v[182:185], v[108:111]
	v_mfma_f32_16x16x32_bf16 v[96:99], v[150:153], v[190:193], v[96:99]
	v_mfma_f32_16x16x32_bf16 v[92:95], v[158:161], v[190:193], v[92:95]
	v_mfma_f32_16x16x32_bf16 v[80:83], v[150:153], v[198:201], v[80:83]
	v_mfma_f32_16x16x32_bf16 v[76:79], v[158:161], v[198:201], v[76:79]
	v_mfma_f32_16x16x32_bf16 v[128:131], v[154:157], v[170:173], v[128:131]
	v_mfma_f32_16x16x32_bf16 v[124:127], v[162:165], v[170:173], v[124:127]
	v_mfma_f32_16x16x32_bf16 v[112:115], v[154:157], v[186:189], v[112:115]
	v_mfma_f32_16x16x32_bf16 v[108:111], v[162:165], v[186:189], v[108:111]
	v_mfma_f32_16x16x32_bf16 v[96:99], v[154:157], v[194:197], v[96:99]
	v_mfma_f32_16x16x32_bf16 v[92:95], v[162:165], v[194:197], v[92:95]
	v_mfma_f32_16x16x32_bf16 v[80:83], v[154:157], v[202:205], v[80:83]
	v_mfma_f32_16x16x32_bf16 v[76:79], v[162:165], v[202:205], v[76:79]
	s_setprio 0
	s_barrier
	s_mov_b32 m0, s75
	v_add_u32_e32 v56, s72, v139
	v_lshl_add_u64 v[174:175], s[36:37], 0, v[134:135]
	ds_read_b128 v[206:209], v56
	ds_read_b128 v[214:217], v56 offset:1024
	ds_read_b128 v[218:221], v56 offset:2048
	ds_read_b128 v[222:225], v56 offset:3072
	global_load_lds_dwordx4 v[174:175], off
	v_lshl_add_u64 v[226:227], s[36:37], 0, v[136:137]
	s_mov_b32 m0, s76
	s_nop 0
	global_load_lds_dwordx4 v[226:227], off
	s_barrier
	s_waitcnt lgkmcnt(0)
	s_setprio 1
	v_mfma_f32_16x16x32_bf16 v[120:123], v[206:209], v[166:169], v[120:123]
	v_mfma_f32_16x16x32_bf16 v[116:119], v[218:221], v[166:169], v[116:119]
	v_mfma_f32_16x16x32_bf16 v[104:107], v[206:209], v[182:185], v[104:107]
	v_mfma_f32_16x16x32_bf16 v[100:103], v[218:221], v[182:185], v[100:103]
	v_mfma_f32_16x16x32_bf16 v[88:91], v[206:209], v[190:193], v[88:91]
	v_mfma_f32_16x16x32_bf16 v[84:87], v[218:221], v[190:193], v[84:87]
	v_mfma_f32_16x16x32_bf16 v[72:75], v[206:209], v[198:201], v[72:75]
	v_mfma_f32_16x16x32_bf16 v[68:71], v[218:221], v[198:201], v[68:71]
	v_mfma_f32_16x16x32_bf16 v[120:123], v[214:217], v[170:173], v[120:123]
	v_mfma_f32_16x16x32_bf16 v[116:119], v[222:225], v[170:173], v[116:119]
	v_mfma_f32_16x16x32_bf16 v[104:107], v[214:217], v[186:189], v[104:107]
	v_mfma_f32_16x16x32_bf16 v[100:103], v[222:225], v[186:189], v[100:103]
	v_mfma_f32_16x16x32_bf16 v[88:91], v[214:217], v[194:197], v[88:91]
	v_mfma_f32_16x16x32_bf16 v[84:87], v[222:225], v[194:197], v[84:87]
	v_mfma_f32_16x16x32_bf16 v[72:75], v[214:217], v[202:205], v[72:75]
	v_mfma_f32_16x16x32_bf16 v[68:71], v[222:225], v[202:205], v[68:71]
	s_setprio 0
	s_mov_b32 m0, s44
	v_lshl_add_u64 v[228:229], s[38:39], 0, v[134:135]
	s_barrier
	ds_read_b128 v[166:169], v133 offset:16384
	ds_read_b128 v[170:173], v133 offset:17408
	ds_read_b128 v[182:185], v133 offset:18432
	ds_read_b128 v[186:189], v133 offset:19456
	ds_read_b128 v[190:193], v133 offset:20480
	ds_read_b128 v[194:197], v133 offset:21504
	ds_read_b128 v[198:201], v133 offset:22528
	ds_read_b128 v[202:205], v133 offset:23552
	global_load_lds_dwordx4 v[228:229], off
	v_lshl_add_u64 v[230:231], s[38:39], 0, v[136:137]
	s_mov_b32 m0, s45
	s_nop 0
	global_load_lds_dwordx4 v[230:231], off
	s_barrier
	s_waitcnt lgkmcnt(0)
	s_setprio 1
	v_mfma_f32_16x16x32_bf16 v[64:67], v[150:153], v[166:169], v[64:67]
	v_mfma_f32_16x16x32_bf16 v[60:63], v[158:161], v[166:169], v[60:63]
	v_mfma_f32_16x16x32_bf16 v[44:47], v[150:153], v[182:185], v[44:47]
	v_mfma_f32_16x16x32_bf16 v[40:43], v[158:161], v[182:185], v[40:43]
	v_mfma_f32_16x16x32_bf16 v[28:31], v[150:153], v[190:193], v[28:31]
	v_mfma_f32_16x16x32_bf16 v[24:27], v[158:161], v[190:193], v[24:27]
	v_mfma_f32_16x16x32_bf16 v[12:15], v[150:153], v[198:201], v[12:15]
	v_mfma_f32_16x16x32_bf16 v[8:11], v[158:161], v[198:201], v[8:11]
	v_mfma_f32_16x16x32_bf16 v[64:67], v[154:157], v[170:173], v[64:67]
	v_mfma_f32_16x16x32_bf16 v[60:63], v[162:165], v[170:173], v[60:63]
	v_mfma_f32_16x16x32_bf16 v[44:47], v[154:157], v[186:189], v[44:47]
	v_mfma_f32_16x16x32_bf16 v[40:43], v[162:165], v[186:189], v[40:43]
	v_mfma_f32_16x16x32_bf16 v[28:31], v[154:157], v[194:197], v[28:31]
	v_mfma_f32_16x16x32_bf16 v[24:27], v[162:165], v[194:197], v[24:27]
	v_mfma_f32_16x16x32_bf16 v[12:15], v[154:157], v[202:205], v[12:15]
	v_mfma_f32_16x16x32_bf16 v[8:11], v[162:165], v[202:205], v[8:11]
	s_setprio 0
	s_barrier
	s_add_u32 s90, s36, 0x100000
	s_addc_u32 s91, s37, 0
	s_mov_b32 m0, s77
	v_lshl_add_u64 v[150:151], s[90:91], 0, v[134:135]
	global_load_lds_dwordx4 v[150:151], off
	v_lshl_add_u64 v[150:151], s[90:91], 0, v[136:137]
	s_mov_b32 m0, s78
	s_nop 0
	global_load_lds_dwordx4 v[150:151], off
	s_waitcnt vmcnt(6)
	s_barrier
	s_setprio 1
	v_mfma_f32_16x16x32_bf16 v[52:55], v[206:209], v[166:169], v[52:55]
	v_mfma_f32_16x16x32_bf16 v[48:51], v[218:221], v[166:169], v[48:51]
	v_mfma_f32_16x16x32_bf16 v[36:39], v[206:209], v[182:185], v[36:39]
	v_mfma_f32_16x16x32_bf16 v[32:35], v[218:221], v[182:185], v[32:35]
	v_mfma_f32_16x16x32_bf16 v[20:23], v[206:209], v[190:193], v[20:23]
	v_mfma_f32_16x16x32_bf16 v[16:19], v[218:221], v[190:193], v[16:19]
	v_mfma_f32_16x16x32_bf16 v[4:7], v[206:209], v[198:201], v[4:7]
	v_mfma_f32_16x16x32_bf16 v[0:3], v[218:221], v[198:201], v[0:3]
	v_mfma_f32_16x16x32_bf16 v[52:55], v[214:217], v[170:173], v[52:55]
	v_mfma_f32_16x16x32_bf16 v[48:51], v[222:225], v[170:173], v[48:51]
	v_mfma_f32_16x16x32_bf16 v[36:39], v[214:217], v[186:189], v[36:39]
	v_mfma_f32_16x16x32_bf16 v[32:35], v[222:225], v[186:189], v[32:35]
	v_mfma_f32_16x16x32_bf16 v[20:23], v[214:217], v[194:197], v[20:23]
	v_mfma_f32_16x16x32_bf16 v[16:19], v[222:225], v[194:197], v[16:19]
	v_mfma_f32_16x16x32_bf16 v[4:7], v[214:217], v[202:205], v[4:7]
	v_mfma_f32_16x16x32_bf16 v[0:3], v[222:225], v[202:205], v[0:3]
	s_setprio 0
	v_add_u32_e32 v56, s79, v139
	s_barrier
	ds_read_b128 v[150:153], v56
	ds_read_b128 v[154:157], v56 offset:1024
	ds_read_b128 v[158:161], v56 offset:2048
	ds_read_b128 v[162:165], v56 offset:3072
	s_add_u32 s38, s38, 0x100000
	s_addc_u32 s39, s39, 0
	s_mov_b32 m0, s46
	v_lshl_add_u64 v[206:207], s[38:39], 0, v[134:135]
	ds_read_b128 v[166:169], v133 offset:32768
	ds_read_b128 v[170:173], v133 offset:33792
	ds_read_b128 v[182:185], v133 offset:34816
	ds_read_b128 v[186:189], v133 offset:35840
	ds_read_b128 v[190:193], v133 offset:36864
	ds_read_b128 v[194:197], v133 offset:37888
	ds_read_b128 v[198:201], v133 offset:38912
	ds_read_b128 v[202:205], v133 offset:39936
	global_load_lds_dwordx4 v[206:207], off
	v_lshl_add_u64 v[206:207], s[38:39], 0, v[136:137]
	s_mov_b32 m0, s47
	s_nop 0
	global_load_lds_dwordx4 v[206:207], off
	s_waitcnt lgkmcnt(8)
	s_barrier
	s_waitcnt lgkmcnt(0)
	s_setprio 1
	v_mfma_f32_16x16x32_bf16 v[128:131], v[150:153], v[166:169], v[128:131]
	v_mfma_f32_16x16x32_bf16 v[124:127], v[158:161], v[166:169], v[124:127]
	v_mfma_f32_16x16x32_bf16 v[112:115], v[150:153], v[182:185], v[112:115]
	v_mfma_f32_16x16x32_bf16 v[108:111], v[158:161], v[182:185], v[108:111]
	v_mfma_f32_16x16x32_bf16 v[96:99], v[150:153], v[190:193], v[96:99]
	v_mfma_f32_16x16x32_bf16 v[92:95], v[158:161], v[190:193], v[92:95]
	v_mfma_f32_16x16x32_bf16 v[80:83], v[150:153], v[198:201], v[80:83]
	v_mfma_f32_16x16x32_bf16 v[76:79], v[158:161], v[198:201], v[76:79]
	v_mfma_f32_16x16x32_bf16 v[128:131], v[154:157], v[170:173], v[128:131]
	v_mfma_f32_16x16x32_bf16 v[124:127], v[162:165], v[170:173], v[124:127]
	v_mfma_f32_16x16x32_bf16 v[112:115], v[154:157], v[186:189], v[112:115]
	v_mfma_f32_16x16x32_bf16 v[108:111], v[162:165], v[186:189], v[108:111]
	v_mfma_f32_16x16x32_bf16 v[96:99], v[154:157], v[194:197], v[96:99]
	v_mfma_f32_16x16x32_bf16 v[92:95], v[162:165], v[194:197], v[92:95]
	v_mfma_f32_16x16x32_bf16 v[80:83], v[154:157], v[202:205], v[80:83]
	v_mfma_f32_16x16x32_bf16 v[76:79], v[162:165], v[202:205], v[76:79]
	s_setprio 0
	s_barrier
	s_add_i32 s3, 0, 0x1c000
	s_add_i32 s38, s79, s41
	v_add_u32_e32 v56, s3, v139
	v_lshl_add_u64 v[174:175], v[174:175], 0, s[16:17]
	s_mov_b32 m0, s38
	ds_read_b128 v[206:209], v56
	ds_read_b128 v[214:217], v56 offset:1024
	ds_read_b128 v[218:221], v56 offset:2048
	ds_read_b128 v[222:225], v56 offset:3072
	global_load_lds_dwordx4 v[174:175], off
	v_lshl_add_u64 v[174:175], v[226:227], 0, s[16:17]
	s_add_i32 m0, s38, 0x2000
	s_nop 0
	global_load_lds_dwordx4 v[174:175], off
	s_barrier
	s_waitcnt lgkmcnt(0)
	s_setprio 1
	v_mfma_f32_16x16x32_bf16 v[120:123], v[206:209], v[166:169], v[120:123]
	v_mfma_f32_16x16x32_bf16 v[116:119], v[218:221], v[166:169], v[116:119]
	v_mfma_f32_16x16x32_bf16 v[104:107], v[206:209], v[182:185], v[104:107]
	v_mfma_f32_16x16x32_bf16 v[100:103], v[218:221], v[182:185], v[100:103]
	v_mfma_f32_16x16x32_bf16 v[88:91], v[206:209], v[190:193], v[88:91]
	v_mfma_f32_16x16x32_bf16 v[84:87], v[218:221], v[190:193], v[84:87]
	v_mfma_f32_16x16x32_bf16 v[72:75], v[206:209], v[198:201], v[72:75]
	v_mfma_f32_16x16x32_bf16 v[68:71], v[218:221], v[198:201], v[68:71]
	v_mfma_f32_16x16x32_bf16 v[120:123], v[214:217], v[170:173], v[120:123]
	v_mfma_f32_16x16x32_bf16 v[116:119], v[222:225], v[170:173], v[116:119]
	v_mfma_f32_16x16x32_bf16 v[104:107], v[214:217], v[186:189], v[104:107]
	v_mfma_f32_16x16x32_bf16 v[100:103], v[222:225], v[186:189], v[100:103]
	v_mfma_f32_16x16x32_bf16 v[88:91], v[214:217], v[194:197], v[88:91]
	v_mfma_f32_16x16x32_bf16 v[84:87], v[222:225], v[194:197], v[84:87]
	v_mfma_f32_16x16x32_bf16 v[72:75], v[214:217], v[202:205], v[72:75]
	v_mfma_f32_16x16x32_bf16 v[68:71], v[222:225], v[202:205], v[68:71]
	s_setprio 0
	s_mov_b32 m0, s67
	v_lshl_add_u64 v[174:175], v[228:229], 0, s[16:17]
	s_barrier
	ds_read_b128 v[166:169], v133 offset:49152
	ds_read_b128 v[170:173], v133 offset:50176
	ds_read_b128 v[182:185], v133 offset:51200
	ds_read_b128 v[186:189], v133 offset:52224
	ds_read_b128 v[190:193], v133 offset:53248
	ds_read_b128 v[194:197], v133 offset:54272
	ds_read_b128 v[198:201], v133 offset:55296
	ds_read_b128 v[202:205], v133 offset:56320
	global_load_lds_dwordx4 v[174:175], off
	v_lshl_add_u64 v[174:175], v[230:231], 0, s[16:17]
	s_mov_b32 m0, s68
	s_nop 0
	global_load_lds_dwordx4 v[174:175], off
	s_barrier
	s_waitcnt lgkmcnt(0)
	s_setprio 1
	v_mfma_f32_16x16x32_bf16 v[64:67], v[150:153], v[166:169], v[64:67]
	v_mfma_f32_16x16x32_bf16 v[60:63], v[158:161], v[166:169], v[60:63]
	v_mfma_f32_16x16x32_bf16 v[44:47], v[150:153], v[182:185], v[44:47]
	v_mfma_f32_16x16x32_bf16 v[40:43], v[158:161], v[182:185], v[40:43]
	v_mfma_f32_16x16x32_bf16 v[28:31], v[150:153], v[190:193], v[28:31]
	v_mfma_f32_16x16x32_bf16 v[24:27], v[158:161], v[190:193], v[24:27]
	v_mfma_f32_16x16x32_bf16 v[12:15], v[150:153], v[198:201], v[12:15]
	v_mfma_f32_16x16x32_bf16 v[8:11], v[158:161], v[198:201], v[8:11]
	v_mfma_f32_16x16x32_bf16 v[64:67], v[154:157], v[170:173], v[64:67]
	v_mfma_f32_16x16x32_bf16 v[60:63], v[162:165], v[170:173], v[60:63]
	v_mfma_f32_16x16x32_bf16 v[44:47], v[154:157], v[186:189], v[44:47]
	v_mfma_f32_16x16x32_bf16 v[40:43], v[162:165], v[186:189], v[40:43]
	v_mfma_f32_16x16x32_bf16 v[28:31], v[154:157], v[194:197], v[28:31]
	v_mfma_f32_16x16x32_bf16 v[24:27], v[162:165], v[194:197], v[24:27]
	v_mfma_f32_16x16x32_bf16 v[12:15], v[154:157], v[202:205], v[12:15]
	v_mfma_f32_16x16x32_bf16 v[8:11], v[162:165], v[202:205], v[8:11]
	s_setprio 0
	s_barrier
	s_add_u32 s36, s36, 0x100080
	s_addc_u32 s37, s37, 0
	s_add_i32 s3, s3, s41
	v_lshl_add_u64 v[150:151], s[36:37], 0, v[134:135]
	s_mov_b32 m0, s3
	s_nop 0
	global_load_lds_dwordx4 v[150:151], off
	v_lshl_add_u64 v[150:151], s[36:37], 0, v[136:137]
	s_add_i32 m0, s3, 0x2000
	s_nop 0
	global_load_lds_dwordx4 v[150:151], off
	s_waitcnt vmcnt(6)
	s_barrier
	s_setprio 1
	v_mfma_f32_16x16x32_bf16 v[52:55], v[206:209], v[166:169], v[52:55]
	v_mfma_f32_16x16x32_bf16 v[48:51], v[218:221], v[166:169], v[48:51]
	v_mfma_f32_16x16x32_bf16 v[36:39], v[206:209], v[182:185], v[36:39]
	v_mfma_f32_16x16x32_bf16 v[32:35], v[218:221], v[182:185], v[32:35]
	v_mfma_f32_16x16x32_bf16 v[20:23], v[206:209], v[190:193], v[20:23]
	v_mfma_f32_16x16x32_bf16 v[16:19], v[218:221], v[190:193], v[16:19]
	v_mfma_f32_16x16x32_bf16 v[4:7], v[206:209], v[198:201], v[4:7]
	v_mfma_f32_16x16x32_bf16 v[0:3], v[218:221], v[198:201], v[0:3]
	v_mfma_f32_16x16x32_bf16 v[52:55], v[214:217], v[170:173], v[52:55]
	v_mfma_f32_16x16x32_bf16 v[48:51], v[222:225], v[170:173], v[48:51]
	v_mfma_f32_16x16x32_bf16 v[36:39], v[214:217], v[186:189], v[36:39]
	v_mfma_f32_16x16x32_bf16 v[32:35], v[222:225], v[186:189], v[32:35]
	v_mfma_f32_16x16x32_bf16 v[20:23], v[214:217], v[194:197], v[20:23]
	v_mfma_f32_16x16x32_bf16 v[16:19], v[222:225], v[194:197], v[16:19]
	v_mfma_f32_16x16x32_bf16 v[4:7], v[214:217], v[202:205], v[4:7]
	v_mfma_f32_16x16x32_bf16 v[0:3], v[222:225], v[202:205], v[0:3]
	s_setprio 0
	s_add_u32 s34, s34, 0x100
	s_addc_u32 s35, s35, 0
	s_cmp_ge_u32 s89, s49
	s_barrier
	s_cbranch_scc0 .LBB0_640
	s_add_u32 s34, s83, 0xffffff00
	s_addc_u32 s35, s84, -1
	s_and_b64 vcc, exec, s[28:29]
	s_cbranch_vccnz .LBB0_638
	s_mov_b64 s[8:9], s[34:35]
	s_andn2_b64 vcc, exec, s[20:21]
	s_cbranch_vccnz .LBB0_639
